# scan chunk loop: raw staging ring 2->3 LDS buffers, LDS-DMA issued two chunks ahead, closing wait leaves that chunk in flight
# speedup vs baseline: 1.0079x; 1.0079x over previous
.LBB0_397:
	v_add_u32_e32 v0, 32, v130
	v_subrev_u32_e32 v1, 32, v131
	v_cndmask_b32_e64 v0, v1, v0, s[76:77]
	v_ashrrev_i32_e32 v1, 31, v0
	v_lshl_add_u64 v[0:1], s[82:83], 0, v[0:1]
	v_lshlrev_b64 v[0:1], 12, v[0:1]
	s_add_i32 m0, s26, 0x5200
	v_lshl_add_u64 v[2:3], v[118:119], 0, v[0:1]
	global_load_lds_dwordx4 v[2:3], off
	v_lshl_add_u64 v[0:1], v[120:121], 0, v[0:1]
	s_add_i32 m0, s11, 0x5200
	s_nop 0
	global_load_lds_dwordx4 v[0:1], off
	s_and_b64 vcc, exec, s[78:79]
	s_cbranch_vccnz .Lsc_p1
	v_add_u32_e32 v0, 32, v132
	v_subrev_u32_e32 v1, 32, v133
	v_cndmask_b32_e64 v0, v1, v0, s[76:77]
	v_ashrrev_i32_e32 v1, 31, v0
	v_lshl_add_u64 v[0:1], s[82:83], 0, v[0:1]
	v_lshlrev_b64 v[0:1], 12, v[0:1]
	v_lshl_add_u64 v[0:1], v[122:123], 0, v[0:1]
	s_add_i32 m0, s88, 0x5200
	s_nop 0
	global_load_lds_dwordx4 v[0:1], off
.Lsc_p1:
	s_lshl_b32 s18, s3, 6
	s_and_b64 s[16:17], s[76:77], exec
	s_mov_b32 s3, 0x17500000
	s_cselect_b32 s16, s3, 0x1b900000
	s_add_u32 s16, s28, s16
	s_addc_u32 s17, s29, 0
	s_lshl_b32 s80, s18, 1
	s_add_u32 s20, s16, s80
	s_addc_u32 s21, s17, 0
	s_add_u32 s34, s20, s2
	s_addc_u32 s35, s21, 0
	s_lshl_b64 s[20:21], s[8:9], 1
	s_waitcnt vmcnt(0)
	s_add_u32 s20, s34, s20
	v_mov_b32_e32 v14, v177
	v_mov_b32_e32 v15, v177
	s_addc_u32 s21, s35, s21
	v_lshlrev_b32_e32 v124, 1, v114
	v_mov_b32_e32 v125, v177
	v_mov_b32_e32 v0, v177
	v_mov_b32_e32 v1, v177
	v_mov_b32_e32 v2, v177
	v_mov_b32_e32 v3, v177
	v_mov_b32_e32 v4, v177
	v_mov_b32_e32 v5, v177
	v_mov_b32_e32 v6, v177
	v_mov_b32_e32 v7, v177
	v_mov_b32_e32 v8, v177
	v_mov_b32_e32 v9, v177
	v_mov_b32_e32 v10, v177
	v_mov_b32_e32 v11, v177
	v_mov_b32_e32 v12, v177
	v_mov_b32_e32 v13, v177
	v_mov_b64_e32 v[30:31], v[14:15]
	v_mov_b64_e32 v[46:47], v[14:15]
	v_mov_b64_e32 v[62:63], v[14:15]
	v_mov_b64_e32 v[78:79], v[14:15]
	s_mov_b32 s3, 0
	s_mov_b32 s24, 1
	s_mov_b32 s98, 0
	s_mov_b32 s99, 0x5200
	s_mov_b32 s100, 0x14000
	v_lshl_add_u64 v[126:127], s[20:21], 0, v[124:125]
	v_mov_b32_e32 v117, v173
	v_mov_b32_e32 v125, v171
	v_mov_b32_e32 v180, v169
	v_mov_b64_e32 v[28:29], v[12:13]
	v_mov_b64_e32 v[26:27], v[10:11]
	v_mov_b64_e32 v[24:25], v[8:9]
	v_mov_b64_e32 v[22:23], v[6:7]
	v_mov_b64_e32 v[20:21], v[4:5]
	v_mov_b64_e32 v[18:19], v[2:3]
	v_mov_b64_e32 v[16:17], v[0:1]
	v_mov_b64_e32 v[44:45], v[12:13]
	v_mov_b64_e32 v[42:43], v[10:11]
	v_mov_b64_e32 v[40:41], v[8:9]
	v_mov_b64_e32 v[38:39], v[6:7]
	v_mov_b64_e32 v[36:37], v[4:5]
	v_mov_b64_e32 v[34:35], v[2:3]
	v_mov_b64_e32 v[32:33], v[0:1]
	v_mov_b64_e32 v[60:61], v[12:13]
	v_mov_b64_e32 v[58:59], v[10:11]
	v_mov_b64_e32 v[56:57], v[8:9]
	v_mov_b64_e32 v[54:55], v[6:7]
	v_mov_b64_e32 v[52:53], v[4:5]
	v_mov_b64_e32 v[50:51], v[2:3]
	v_mov_b64_e32 v[48:49], v[0:1]
	v_mov_b64_e32 v[76:77], v[12:13]
	v_mov_b64_e32 v[74:75], v[10:11]
	v_mov_b64_e32 v[72:73], v[8:9]
	v_mov_b64_e32 v[70:71], v[6:7]
	v_mov_b64_e32 v[68:69], v[4:5]
	v_mov_b64_e32 v[66:67], v[2:3]
	v_mov_b64_e32 v[64:65], v[0:1]
	s_waitcnt vmcnt(0) lgkmcnt(0)
	s_barrier
	s_branch .LBB0_399
.LBB0_398:
	s_cmpk_gt_u32 s3, 0x10bf
	s_cbranch_scc1 .Lsw_0
	s_cmp_lg_u64 s[14:15], 0
	s_cbranch_scc1 .Lsw_7
	s_cmp_lg_u64 s[78:79], 0
	s_cbranch_scc1 .Lsw_2
	s_waitcnt vmcnt(3)
	s_branch .Lsw_d
.Lsw_2:
	s_waitcnt vmcnt(2)
	s_branch .Lsw_d
.Lsw_7:
	s_waitcnt vmcnt(7)
	s_branch .Lsw_d

.Lsw_d:
	s_add_i32 s3, s3, 32
	s_mov_b32 s101, s98
	s_mov_b32 s98, s99
	s_mov_b32 s99, s100
	s_mov_b32 s100, s101
	s_add_i32 s24, s24, 1
	v_subrev_u32_e32 v180, 32, v180
	v_subrev_u32_e32 v125, 32, v125
	s_cmpk_eq_i32 s3, 0x1100
	v_subrev_u32_e32 v117, 32, v117
	s_waitcnt lgkmcnt(0)
	s_barrier
	s_cbranch_scc1 .LBB0_414
.LBB0_399:
	s_cmpk_gt_u32 s3, 0x10bf
	s_cbranch_scc1 .LBB0_402
	v_add_u32_e32 v80, s3, v172
	v_add_u32_e32 v80, 32, v80
	v_cmp_lt_i32_e32 vcc, s33, v80
	s_mov_b32 s20, s100
	v_cndmask_b32_e32 v81, v207, v208, vcc
	v_add_u32_e32 v81, v81, v117
	v_subrev_u32_e32 v81, 32, v81
	v_cndmask_b32_e64 v80, v81, v80, s[76:77]
	v_ashrrev_i32_e32 v81, 31, v80
	v_lshl_add_u64 v[80:81], s[82:83], 0, v[80:81]
	v_lshlrev_b64 v[80:81], 12, v[80:81]
	s_add_i32 s21, s20, s26
	v_lshl_add_u64 v[82:83], v[118:119], 0, v[80:81]
	s_mov_b32 m0, s21
	v_lshl_add_u64 v[80:81], v[120:121], 0, v[80:81]
	global_load_lds_dwordx4 v[82:83], off
	s_add_i32 m0, s21, 0x2080
	s_and_b64 vcc, exec, s[78:79]
	global_load_lds_dwordx4 v[80:81], off
	s_cbranch_vccnz .LBB0_402
	v_add_u32_e32 v80, s3, v170
	v_add_u32_e32 v80, 32, v80
	v_cmp_lt_i32_e32 vcc, s33, v80
	s_add_i32 s20, s20, s6
	s_add_i32 m0, s20, 0x4100
	v_cndmask_b32_e32 v81, v207, v208, vcc
	v_add_u32_e32 v81, v81, v125
	v_subrev_u32_e32 v81, 32, v81
	v_cndmask_b32_e64 v80, v81, v80, s[76:77]
	v_ashrrev_i32_e32 v81, 31, v80
	v_lshl_add_u64 v[80:81], s[82:83], 0, v[80:81]
	v_lshlrev_b64 v[80:81], 12, v[80:81]
	v_lshl_add_u64 v[80:81], v[122:123], 0, v[80:81]
	global_load_lds_dwordx4 v[80:81], off

.LBB0_404:
	s_mov_b32 s20, s98
	v_add_u32_e32 v80, s20, v145
	ds_read_u16 v81, v80 offset:8320
	ds_read_u16 v82, v80
	ds_read_u16 v83, v80 offset:8576
	ds_read_u16 v84, v80 offset:8832
	ds_read_u16 v85, v80 offset:9088
	ds_read_u16 v86, v80 offset:768
	s_waitcnt lgkmcnt(0)
	v_lshlrev_b32_e32 v81, 16, v81
	ds_read_u16 v87, v80 offset:512
	ds_read_u16 v91, v80 offset:256
	v_add_f32_e32 v90, 0, v81
	v_mul_f32_e32 v80, 0x3fb8aa3b, v81
	v_lshlrev_b32_e32 v83, 16, v83
	v_lshlrev_b32_e32 v93, 16, v82
	v_exp_f32_e32 v82, v80
	v_add_f32_e32 v94, v90, v83
	v_lshlrev_b32_e32 v80, 16, v84
	v_add_f32_e32 v96, v94, v80
	v_mul_f32_e32 v80, 0x3fb8aa3b, v80
	v_exp_f32_e32 v84, v80
	v_lshlrev_b32_e32 v80, 16, v85
	s_waitcnt lgkmcnt(0)
	v_lshlrev_b32_e32 v95, 16, v87
	v_add_u32_e32 v81, s20, v146
	v_add_u32_e32 v85, s20, v166
	v_add_u32_e32 v87, s20, v168
	v_add_f32_e32 v101, v96, v80
	v_mul_f32_e32 v80, 0x3fb8aa3b, v80
	v_lshlrev_b32_e32 v97, 16, v86
	v_add_u32_e32 v86, s20, v167
	ds_read_u16 v88, v81 offset:8320
	ds_read_u16 v89, v85 offset:8576
	ds_read_u16 v92, v86 offset:8832
	ds_read_u16 v98, v87 offset:9088
	ds_read_u16 v99, v87 offset:768
	ds_read_u16 v100, v86 offset:512
	ds_read_u16 v87, v85 offset:256
	ds_read_u16 v81, v81
	v_exp_f32_e32 v85, v80
	s_waitcnt lgkmcnt(0)
	v_lshlrev_b32_e32 v80, 16, v88
	v_add_f32_e32 v103, v101, v80
	v_mul_f32_e32 v80, 0x3fb8aa3b, v80
	v_exp_f32_e32 v86, v80
	v_lshlrev_b32_e32 v80, 16, v89
	v_add_f32_e32 v105, v103, v80
	v_mul_f32_e32 v80, 0x3fb8aa3b, v80
	v_lshlrev_b32_e32 v104, 16, v87
	v_exp_f32_e32 v87, v80
	v_lshlrev_b32_e32 v80, 16, v92
	v_add_f32_e32 v106, v105, v80
	v_mul_f32_e32 v80, 0x3fb8aa3b, v80
	v_exp_f32_e32 v88, v80
	v_lshlrev_b32_e32 v80, 16, v98
	v_lshlrev_b32_e32 v102, 16, v81
	v_add_f32_e32 v81, v106, v80
	v_mul_f32_e32 v80, 0x3fb8aa3b, v80
	v_exp_f32_e32 v89, v80
	v_lshlrev_b32_e32 v98, 16, v99
	v_add_f32_dpp v80, v81, v81 quad_perm:[0,0,1,2] row_mask:0xf bank_mask:0xf bound_ctrl:1
	v_cndmask_b32_e64 v80, v80, v81, s[0:1]
	v_mul_f32_e32 v83, 0x3fb8aa3b, v83
	v_exp_f32_e32 v83, v83
	v_add_f32_dpp v92, v80, v80 quad_perm:[0,1,0,1] row_mask:0xf bank_mask:0xf bound_ctrl:1
	v_cndmask_b32_e64 v80, v80, v92, s[38:39]
	v_sub_f32_e32 v99, v80, v81
	v_add_f32_e32 v107, v81, v99
	v_add_f32_e32 v90, v90, v99
	v_mov_b32_dpp v80, v80 quad_perm:[3,3,3,3] row_mask:0xf bank_mask:0xf bound_ctrl:1
	v_mov_b32_dpp v81, v107 quad_perm:[1,1,1,1] row_mask:0xf bank_mask:0xf bound_ctrl:1
	v_sub_f32_e32 v90, v90, v81
	v_mul_f32_e32 v90, 0x3fb8aa3b, v90
	v_exp_f32_e32 v108, v90
	v_sub_f32_e32 v90, v80, v81
	v_mul_f32_e32 v90, 0x3fb8aa3b, v90
	v_exp_f32_e32 v90, v90
	v_mul_f32_e32 v93, v108, v93
	v_cvt_pk_bf16_f32 v93, v93, s0
	ds_write_b16 v147, v93 offset:41984
	v_add_f32_e32 v93, v94, v99
	v_sub_f32_e32 v93, v93, v81
	v_mul_f32_e32 v93, 0x3fb8aa3b, v93
	v_exp_f32_e32 v94, v93
	v_rcp_f32_e32 v92, v108
	v_lshlrev_b32_e32 v91, 16, v91
	v_pk_add_f32 v[82:83], v[82:83], 1.0 op_sel_hi:[1,0] neg_lo:[1,0] neg_hi:[1,0]
	v_rcp_f32_e32 v93, v94
	v_mul_f32_e32 v91, v94, v91
	v_cvt_pk_bf16_f32 v91, v91, s0
	v_pk_add_f32 v[84:85], v[84:85], 1.0 op_sel_hi:[1,0] neg_lo:[1,0] neg_hi:[1,0]
	v_pk_mul_f32 v[82:83], v[82:83], v[92:93]
	v_pk_add_f32 v[86:87], v[86:87], 1.0 op_sel_hi:[1,0] neg_lo:[1,0] neg_hi:[1,0]
	v_cvt_pk_bf16_f32 v92, v82, s0
	ds_write_b16 v147, v92 offset:50176
	ds_write_b16 v148, v91 offset:41984
	v_cvt_pk_bf16_f32 v91, v83, s0
	v_pk_mul_f32 v[82:83], v[90:91], v[82:83] op_sel_hi:[0,1]
	v_add_f32_e32 v92, v96, v99
	v_cvt_pk_bf16_f32 v82, v82, v83
	v_add_f32_e32 v83, v101, v99
	v_sub_f32_e32 v92, v92, v81
	v_sub_f32_e32 v83, v83, v81
	v_mul_f32_e32 v92, 0x3fb8aa3b, v92
	v_mul_f32_e32 v83, 0x3fb8aa3b, v83
	v_exp_f32_e32 v93, v92
	v_exp_f32_e32 v83, v83
	ds_write_b16 v148, v91 offset:50176
	v_lshlrev_b32_e32 v100, 16, v100
	v_rcp_f32_e32 v92, v93
	v_mul_f32_e32 v91, v93, v95
	v_rcp_f32_e32 v93, v83
	v_cvt_pk_bf16_f32 v91, v91, s0
	ds_write_b16 v149, v91 offset:41984
	v_mul_f32_e32 v83, v83, v97
	v_pk_mul_f32 v[84:85], v[84:85], v[92:93]
	v_cvt_pk_bf16_f32 v83, v83, s0
	v_cvt_pk_bf16_f32 v91, v84, s0
	ds_write_b16 v149, v91 offset:50176
	ds_write_b16 v150, v83 offset:41984
	v_add_f32_e32 v91, v103, v99
	v_sub_f32_e32 v91, v91, v81
	v_mul_f32_e32 v91, 0x3fb8aa3b, v91
	v_exp_f32_e32 v91, v91
	v_cvt_pk_bf16_f32 v83, v85, s0
	ds_write_b16 v150, v83 offset:50176
	v_pk_add_f32 v[88:89], v[88:89], 1.0 op_sel_hi:[1,0] neg_lo:[1,0] neg_hi:[1,0]
	v_pk_mul_f32 v[84:85], v[90:91], v[84:85] op_sel_hi:[0,1]
	v_cvt_pk_bf16_f32 v83, v84, v85
	v_add_f32_e32 v85, v105, v99
	v_sub_f32_e32 v85, v85, v81
	v_mul_f32_e32 v85, 0x3fb8aa3b, v85
	v_exp_f32_e32 v92, v85
	v_mul_f32_e32 v85, v91, v102
	v_cvt_pk_bf16_f32 v85, v85, s0
	v_rcp_f32_e32 v84, v91
	ds_write_b16 v151, v85 offset:41984
	v_rcp_f32_e32 v85, v92
	v_mul_f32_e32 v91, v92, v104
	v_cvt_pk_bf16_f32 v91, v91, s0
	v_pk_mul_f32 v[84:85], v[86:87], v[84:85]
	v_add_f32_e32 v87, v106, v99
	v_cvt_pk_bf16_f32 v86, v84, s0
	v_sub_f32_e32 v87, v87, v81
	ds_write_b16 v151, v86 offset:50176
	ds_write_b16 v152, v91 offset:41984
	v_cvt_pk_bf16_f32 v86, v85, s0
	v_mul_f32_e32 v87, 0x3fb8aa3b, v87
	v_pk_mul_f32 v[84:85], v[90:91], v[84:85] op_sel_hi:[0,1]
	v_exp_f32_e32 v87, v87
	v_cvt_pk_bf16_f32 v84, v84, v85
	v_sub_f32_e32 v85, v107, v81
	v_mul_f32_e32 v85, 0x3fb8aa3b, v85
	v_exp_f32_e32 v85, v85
	ds_write_b16 v152, v86 offset:50176
	v_rcp_f32_e32 v86, v87
	v_mul_f32_e32 v87, v87, v100
	v_cvt_pk_bf16_f32 v87, v87, s0
	ds_write_b16 v153, v87 offset:41984
	v_rcp_f32_e32 v87, v85
	v_mul_f32_e32 v85, v85, v98
	v_cvt_pk_bf16_f32 v85, v85, s0
	v_pk_mul_f32 v[86:87], v[88:89], v[86:87]
	s_nop 0
	v_cvt_pk_bf16_f32 v88, v86, s0
	ds_write_b16 v153, v88 offset:50176
	ds_write_b16 v154, v85 offset:41984
	v_cvt_pk_bf16_f32 v85, v87, s0
	v_pk_mul_f32 v[86:87], v[90:91], v[86:87] op_sel_hi:[0,1]
	ds_write_b16 v154, v85 offset:50176
	v_cvt_pk_bf16_f32 v85, v86, v87
	v_add_u32_e32 v86, v135, v136
	ds_write_b128 v86, v[82:85] offset:58368
	s_and_saveexec_b64 vcc, s[0:1]
	s_cbranch_execz .LBB0_406
	v_mul_f32_e32 v81, 0x3fb8aa3b, v81
	v_exp_f32_e32 v81, v81
	v_mul_f32_e32 v80, 0x3fb8aa3b, v80
	v_exp_f32_e32 v80, v80
	v_add_u32_e32 v82, 0x11400, v115
	ds_write_b32 v82, v81
	v_add_u32_e32 v81, 0x11600, v115
	ds_write_b32 v81, v80
